# prep_weights: branch-GEMM weights (matrices 4-6) also converted in the in-projection phase tail, so no wave converts more than four blocks in the LN3+prep_weights phase
# baseline (speedup 1.0000x reference)
; __device__ __forceinline__ void prep_weights(lptr L, const Params& P, int l) {
;     ...
; #pragma unroll 1
;     for (int mi = 0; mi < 14; ++mi) {
;         const float* W; int K, N, mode = 0; bf16_t* WT;
;         switch (mi) {
;             case 0: W = P.in[4] + (size_t)l * DM * 2 * DFF; K = DM; N = 2 * DFF; WT = (bf16_t*)(ws + W_1A); mode = 1; break;
;             case 1: W = P.in[5] + (size_t)l * DFF * DM; K = DFF; N = DM; WT = (bf16_t*)(ws + W_2A); break;
;             case 2: W = P.in[6] + (size_t)l * DM * ZLD; K = DM; N = ZLD; WT = (bf16_t*)(ws + W_Z); break;
;             case 3: W = P.in[18] + (size_t)l * DM * 3 * DM; K = DM; N = 3 * DM; WT = (bf16_t*)(ws + W_G); break;
;             case 4: W = P.in[15] + (size_t)l * 512 * DM; K = 512; N = DM; WT = (bf16_t*)(ws + W_BR); break;
;             case 5: W = P.in[16] + (size_t)l * 512 * DM; K = 512; N = DM; WT = (bf16_t*)(ws + W_BR) + 1 * DM * 512; break;
;             case 6: W = P.in[17] + (size_t)l * 512 * DM; K = 512; N = DM; WT = (bf16_t*)(ws + W_BR) + 2 * DM * 512; break;
;             case 7: W = P.in[20] + (size_t)l * DM * DM; K = DM; N = DM; WT = (bf16_t*)(ws + W_O); break;
;             case 8: W = P.in[23] + (size_t)l * DM * 2 * DFF; K = DM; N = 2 * DFF; WT = (bf16_t*)(ws + W_1B); mode = 1; break;
;             case 9: W = P.in[24] + (size_t)l * DFF * DM; K = DFF; N = DM; WT = (bf16_t*)(ws + W_2B); break;
;             case 10: W = P.in[9] + (size_t)l * 2048 * 256; K = 2048; N = 256; WT = (bf16_t*)(ws + W_C1); break;
;             case 11: W = P.in[11] + (size_t)l * 2048 * 256; K = 2048; N = 256; WT = (bf16_t*)(ws + W_C1) + 256 * 2048; break;
;             case 12: W = P.in[10] + (size_t)l * 256 * 64; K = 256; N = 64; WT = (bf16_t*)(ws + W_C2); break;
;             default: W = P.in[12] + (size_t)l * 256 * 64; K = 256; N = 64; WT = (bf16_t*)(ws + W_C2) + 64 * 256; break;
;         }
;         const int nblk = N / 32, nitems = (K / 64) * nblk;
;         for (int it = gw; it < nitems; it += NGW) {
;             const int kb = it / nblk, nb = it - kb * nblk, n0 = 32 * nb;
;             int drow0 = n0;
;             if (mode == 1) { const int up = n0 >= DFF, nn = up ? n0 - DFF : n0; drow0 = 256 * (nn >> 7) + (up ? 128 : 0) + (nn & 127); }
;             tr_item(W, N, K, 64 * kb, n0, WT, drow0, scr, lane);
;         }
;     }
.LBB0_742:
	s_waitcnt vmcnt(0)
	v_readlane_b32 s36, v255, 11
	s_barrier
	v_readlane_b32 s0, v252, 40
	s_cmpk_lt_u32 s0, 0x400
	s_cbranch_scc1 .Lpw2_done
	v_mov_b32_e32 v13, v193
	v_readlane_b32 s0, v252, 40
	v_bfe_u32 v19, v13, 3, 3
	v_lshlrev_b32_e32 v0, 2, v13
	v_and_b32_e32 v0, 28, v0
	v_mul_u32_u24_e32 v2, 33, v19
	v_add_lshl_u32 v20, v2, v0, 2
	v_lshlrev_b32_e32 v2, 3, v13
	v_and_b32_e32 v2, 56, v2
	v_ashrrev_i32_e32 v3, 6, v13
	v_mul_u32_u24_e32 v6, 33, v2
	v_add_u32_e32 v15, s0, v3
	v_add_u32_e32 v15, 0xfffffc00, v15
	s_movk_i32 s0, 0x2200
	v_or_b32_e32 v21, 8, v19
	v_or_b32_e32 v22, 16, v19
	v_or_b32_e32 v23, 24, v19
	v_or_b32_e32 v8, v6, v19
	v_mul_lo_u32 v18, v3, s0
	v_add_u32_e32 v4, 0x420, v20
	v_add_u32_e32 v5, 0x840, v20
	v_add_u32_e32 v7, 0xc60, v20
	v_lshlrev_b32_e32 v8, 2, v8
	v_add_lshl_u32 v9, v6, v21, 2
	v_add_lshl_u32 v10, v6, v22, 2
	v_add_lshl_u32 v11, v6, v23, 2
	v_readlane_b32 s0, v255, 7
	s_mov_b32 s5, 4
	s_mov_b32 s99, 0
	v_lshlrev_b32_e32 v0, 2, v0
	v_lshl_add_u32 v24, v3, 5, s0
	v_lshlrev_b32_e32 v6, 1, v2
	v_add_u32_e32 v25, v18, v4
	v_add_u32_e32 v26, v18, v5
	v_add_u32_e32 v27, v18, v7
	v_add_u32_e32 v28, v18, v8
	v_add_u32_e32 v29, v18, v9
	v_add_u32_e32 v30, v18, v10
	v_add_u32_e32 v31, v18, v11
	s_branch .Lpw2_884

; __device__ __forceinline__ void prep_weights(lptr L, const Params& P, int l) {
;     ...
; #pragma unroll 1
;     for (int mi = 0; mi < 14; ++mi) {
;         const float* W; int K, N, mode = 0; bf16_t* WT;
;         switch (mi) {
;             case 0: W = P.in[4] + (size_t)l * DM * 2 * DFF; K = DM; N = 2 * DFF; WT = (bf16_t*)(ws + W_1A); mode = 1; break;
;             case 1: W = P.in[5] + (size_t)l * DFF * DM; K = DFF; N = DM; WT = (bf16_t*)(ws + W_2A); break;
;             case 2: W = P.in[6] + (size_t)l * DM * ZLD; K = DM; N = ZLD; WT = (bf16_t*)(ws + W_Z); break;
;             case 3: W = P.in[18] + (size_t)l * DM * 3 * DM; K = DM; N = 3 * DM; WT = (bf16_t*)(ws + W_G); break;
;             case 4: W = P.in[15] + (size_t)l * 512 * DM; K = 512; N = DM; WT = (bf16_t*)(ws + W_BR); break;
;             case 5: W = P.in[16] + (size_t)l * 512 * DM; K = 512; N = DM; WT = (bf16_t*)(ws + W_BR) + 1 * DM * 512; break;
;             case 6: W = P.in[17] + (size_t)l * 512 * DM; K = 512; N = DM; WT = (bf16_t*)(ws + W_BR) + 2 * DM * 512; break;
;             case 7: W = P.in[20] + (size_t)l * DM * DM; K = DM; N = DM; WT = (bf16_t*)(ws + W_O); break;
;             case 8: W = P.in[23] + (size_t)l * DM * 2 * DFF; K = DM; N = 2 * DFF; WT = (bf16_t*)(ws + W_1B); mode = 1; break;
;             case 9: W = P.in[24] + (size_t)l * DFF * DM; K = DFF; N = DM; WT = (bf16_t*)(ws + W_2B); break;
;             case 10: W = P.in[9] + (size_t)l * 2048 * 256; K = 2048; N = 256; WT = (bf16_t*)(ws + W_C1); break;
;             case 11: W = P.in[11] + (size_t)l * 2048 * 256; K = 2048; N = 256; WT = (bf16_t*)(ws + W_C1) + 256 * 2048; break;
;             case 12: W = P.in[10] + (size_t)l * 256 * 64; K = 256; N = 64; WT = (bf16_t*)(ws + W_C2); break;
;             default: W = P.in[12] + (size_t)l * 256 * 64; K = 256; N = 64; WT = (bf16_t*)(ws + W_C2) + 64 * 256; break;
;         }
;         const int nblk = N / 32, nitems = (K / 64) * nblk;
;         for (int it = gw; it < nitems; it += NGW) {
;             const int kb = it / nblk, nb = it - kb * nblk, n0 = 32 * nb;
;             int drow0 = n0;
;             if (mode == 1) { const int up = n0 >= DFF, nn = up ? n0 - DFF : n0; drow0 = 256 * (nn >> 7) + (up ? 128 : 0) + (nn & 127); }
;             tr_item(W, N, K, 64 * kb, n0, WT, drow0, scr, lane);
;         }
;     }
.LBB0_883:
	s_or_b64 exec, exec, s[2:3]
	s_add_i32 s5, s5, 1
	s_cmp_eq_u32 s5, 4
	s_cselect_b32 s5, 10, s5
	s_cmp_eq_u32 s5, 14
	s_cbranch_scc1 .LBB0_937
